# nt (streaming) hint on the P1 C-tile stores so they do not displace operand lines in L2
# speedup vs baseline: 1.0013x; 1.0013x over previous
.Lp1m_kloop:
	s_waitcnt vmcnt(0) lgkmcnt(0)
	s_barrier
	ds_read_b128 v[170:173], v232 offset:24576
	ds_read_b128 v[174:177], v232 offset:26624
	ds_read_b128 v[178:181], v230 offset:24576
	ds_read_b128 v[182:185], v230 offset:26624
	ds_read_b128 v[186:189], v230 offset:28672
	ds_read_b128 v[190:193], v230 offset:30720
	s_setprio 1
	v_mfma_f32_32x32x16_bf16 v[48:63], v[222:225], v[206:209], v[48:63]
	v_mfma_f32_32x32x16_bf16 v[32:47], v[222:225], v[210:213], v[32:47]
	v_mfma_f32_32x32x16_bf16 v[16:31], v[226:229], v[206:209], v[16:31]
	v_mfma_f32_32x32x16_bf16 v[0:15], v[226:229], v[210:213], v[0:15]
	s_setprio 0
	s_add_u32 m0, s101, 0xc000
	s_nop 0
	global_load_lds_dwordx4 v234, s[98:99]
	s_add_u32 m0, s101, 0x0
	s_nop 0
	global_load_lds_dwordx4 v234, s[44:45]
	s_add_u32 m0, s101, 0xc400
	s_nop 0
	global_load_lds_dwordx4 v235, s[98:99]
	s_add_u32 m0, s101, 0x400
	s_nop 0
	global_load_lds_dwordx4 v235, s[44:45]
	s_waitcnt lgkmcnt(2)
	s_setprio 1
	v_mfma_f32_32x32x16_bf16 v[112:127], v[178:181], v[170:173], v[112:127]
	v_mfma_f32_32x32x16_bf16 v[96:111], v[178:181], v[174:177], v[96:111]
	v_mfma_f32_32x32x16_bf16 v[80:95], v[182:185], v[170:173], v[80:95]
	v_mfma_f32_32x32x16_bf16 v[64:79], v[182:185], v[174:177], v[64:79]
	s_setprio 0
	ds_read_b128 v[206:209], v233 offset:24576
	ds_read_b128 v[210:213], v233 offset:26624
	ds_read_b128 v[214:217], v231 offset:24576
	ds_read_b128 v[218:221], v231 offset:26624
	s_add_u32 m0, s101, 0xc800
	s_nop 0
	global_load_lds_dwordx4 v236, s[98:99]
	s_add_u32 m0, s101, 0x800
	s_nop 0
	global_load_lds_dwordx4 v236, s[44:45]
	s_add_u32 m0, s101, 0xcc00
	s_nop 0
	global_load_lds_dwordx4 v237, s[98:99]
	s_add_u32 m0, s101, 0xc00
	s_nop 0
	global_load_lds_dwordx4 v237, s[44:45]
	s_waitcnt lgkmcnt(4)
	s_setprio 1
	v_mfma_f32_32x32x16_bf16 v[48:63], v[186:189], v[170:173], v[48:63]
	v_mfma_f32_32x32x16_bf16 v[32:47], v[186:189], v[174:177], v[32:47]
	v_mfma_f32_32x32x16_bf16 v[16:31], v[190:193], v[170:173], v[16:31]
	v_mfma_f32_32x32x16_bf16 v[0:15], v[190:193], v[174:177], v[0:15]
	s_setprio 0
	ds_read_b128 v[222:225], v231 offset:28672
	ds_read_b128 v[226:229], v231 offset:30720
	v_xad_u32 v241, s36, v240, v238
	v_xad_u32 v242, s37, v240, v239
	s_add_u32 m0, s49, 0xc000
	s_nop 0
	global_load_lds_dwordx4 v241, s[94:95]
	s_add_u32 m0, s49, 0xffffffc0
	s_nop 0
	global_load_lds_dwordx4 v241, s[94:95] offset:64
	s_add_u32 m0, s49, 0xc400
	s_nop 0
	global_load_lds_dwordx4 v242, s[94:95]
	s_add_u32 m0, s49, 0x3c0
	s_nop 0
	global_load_lds_dwordx4 v242, s[94:95] offset:64
	s_add_u32 s36, s36, 0x80
	s_xor_b32 s37, s36, 0x800
	s_add_u32 s98, s98, 128
	s_addc_u32 s99, s99, 0
	s_add_u32 s44, s44, 128
	s_addc_u32 s45, s45, 0
	s_waitcnt lgkmcnt(2)
	s_setprio 1
	v_mfma_f32_32x32x16_bf16 v[112:127], v[214:217], v[206:209], v[112:127]
	v_mfma_f32_32x32x16_bf16 v[96:111], v[214:217], v[210:213], v[96:111]
	v_mfma_f32_32x32x16_bf16 v[80:95], v[218:221], v[206:209], v[80:95]
	v_mfma_f32_32x32x16_bf16 v[64:79], v[218:221], v[210:213], v[64:79]
	s_setprio 0
	s_waitcnt vmcnt(0) lgkmcnt(0)
	s_barrier
	ds_read_b128 v[170:173], v232 offset:49152
	ds_read_b128 v[174:177], v232 offset:51200
	ds_read_b128 v[178:181], v230 offset:49152
	ds_read_b128 v[182:185], v230 offset:51200
	ds_read_b128 v[186:189], v230 offset:53248
	ds_read_b128 v[190:193], v230 offset:55296
	s_setprio 1
	v_mfma_f32_32x32x16_bf16 v[48:63], v[222:225], v[206:209], v[48:63]
	v_mfma_f32_32x32x16_bf16 v[32:47], v[222:225], v[210:213], v[32:47]
	v_mfma_f32_32x32x16_bf16 v[16:31], v[226:229], v[206:209], v[16:31]
	v_mfma_f32_32x32x16_bf16 v[0:15], v[226:229], v[210:213], v[0:15]
	s_setprio 0
	s_waitcnt lgkmcnt(2)
	s_setprio 1
	v_mfma_f32_32x32x16_bf16 v[112:127], v[178:181], v[170:173], v[112:127]
	v_mfma_f32_32x32x16_bf16 v[96:111], v[178:181], v[174:177], v[96:111]
	v_mfma_f32_32x32x16_bf16 v[80:95], v[182:185], v[170:173], v[80:95]
	v_mfma_f32_32x32x16_bf16 v[64:79], v[182:185], v[174:177], v[64:79]
	s_setprio 0
	ds_read_b128 v[206:209], v233 offset:49152
	ds_read_b128 v[210:213], v233 offset:51200
	ds_read_b128 v[214:217], v231 offset:49152
	ds_read_b128 v[218:221], v231 offset:51200
	s_waitcnt lgkmcnt(4)
	s_setprio 1
	v_mfma_f32_32x32x16_bf16 v[48:63], v[186:189], v[170:173], v[48:63]
	v_mfma_f32_32x32x16_bf16 v[32:47], v[186:189], v[174:177], v[32:47]
	v_mfma_f32_32x32x16_bf16 v[16:31], v[190:193], v[170:173], v[16:31]
	v_mfma_f32_32x32x16_bf16 v[0:15], v[190:193], v[174:177], v[0:15]
	s_setprio 0
	ds_read_b128 v[222:225], v231 offset:53248
	ds_read_b128 v[226:229], v231 offset:55296
	s_waitcnt lgkmcnt(2)
	s_setprio 1
	v_mfma_f32_32x32x16_bf16 v[112:127], v[214:217], v[206:209], v[112:127]
	v_mfma_f32_32x32x16_bf16 v[96:111], v[214:217], v[210:213], v[96:111]
	v_mfma_f32_32x32x16_bf16 v[80:95], v[218:221], v[206:209], v[80:95]
	v_mfma_f32_32x32x16_bf16 v[64:79], v[218:221], v[210:213], v[64:79]
	s_setprio 0
	s_waitcnt vmcnt(0) lgkmcnt(0)
	s_barrier
	ds_read_b128 v[170:173], v232 offset:0
	ds_read_b128 v[174:177], v232 offset:2048
	ds_read_b128 v[178:181], v230 offset:0
	ds_read_b128 v[182:185], v230 offset:2048
	ds_read_b128 v[186:189], v230 offset:4096
	ds_read_b128 v[190:193], v230 offset:6144
	s_setprio 1
	v_mfma_f32_32x32x16_bf16 v[48:63], v[222:225], v[206:209], v[48:63]
	v_mfma_f32_32x32x16_bf16 v[32:47], v[222:225], v[210:213], v[32:47]
	v_mfma_f32_32x32x16_bf16 v[16:31], v[226:229], v[206:209], v[16:31]
	v_mfma_f32_32x32x16_bf16 v[0:15], v[226:229], v[210:213], v[0:15]
	s_setprio 0
	s_add_u32 m0, s101, 0x6000
	s_nop 0
	global_load_lds_dwordx4 v234, s[98:99]
	s_add_u32 m0, s101, 0xc000
	s_nop 0
	global_load_lds_dwordx4 v234, s[44:45]
	s_add_u32 m0, s101, 0x6400
	s_nop 0
	global_load_lds_dwordx4 v235, s[98:99]
	s_add_u32 m0, s101, 0xc400
	s_nop 0
	global_load_lds_dwordx4 v235, s[44:45]
	s_waitcnt lgkmcnt(2)
	s_setprio 1
	v_mfma_f32_32x32x16_bf16 v[112:127], v[178:181], v[170:173], v[112:127]
	v_mfma_f32_32x32x16_bf16 v[96:111], v[178:181], v[174:177], v[96:111]
	v_mfma_f32_32x32x16_bf16 v[80:95], v[182:185], v[170:173], v[80:95]
	v_mfma_f32_32x32x16_bf16 v[64:79], v[182:185], v[174:177], v[64:79]
	s_setprio 0
	ds_read_b128 v[206:209], v233 offset:0
	ds_read_b128 v[210:213], v233 offset:2048
	ds_read_b128 v[214:217], v231 offset:0
	ds_read_b128 v[218:221], v231 offset:2048
	s_add_u32 m0, s101, 0x6800
	s_nop 0
	global_load_lds_dwordx4 v236, s[98:99]
	s_add_u32 m0, s101, 0xc800
	s_nop 0
	global_load_lds_dwordx4 v236, s[44:45]
	s_add_u32 m0, s101, 0x6c00
	s_nop 0
	global_load_lds_dwordx4 v237, s[98:99]
	s_add_u32 m0, s101, 0xcc00
	s_nop 0
	global_load_lds_dwordx4 v237, s[44:45]
	s_waitcnt lgkmcnt(4)
	s_setprio 1
	v_mfma_f32_32x32x16_bf16 v[48:63], v[186:189], v[170:173], v[48:63]
	v_mfma_f32_32x32x16_bf16 v[32:47], v[186:189], v[174:177], v[32:47]
	v_mfma_f32_32x32x16_bf16 v[16:31], v[190:193], v[170:173], v[16:31]
	v_mfma_f32_32x32x16_bf16 v[0:15], v[190:193], v[174:177], v[0:15]
	s_setprio 0
	ds_read_b128 v[222:225], v231 offset:4096
	ds_read_b128 v[226:229], v231 offset:6144
	v_xad_u32 v241, s36, v240, v238
	v_xad_u32 v242, s37, v240, v239
	s_add_u32 m0, s49, 0x6000
	s_nop 0
	global_load_lds_dwordx4 v241, s[94:95]
	s_add_u32 m0, s49, 0xbfc0
	s_nop 0
	global_load_lds_dwordx4 v241, s[94:95] offset:64
	s_add_u32 m0, s49, 0x6400
	s_nop 0
	global_load_lds_dwordx4 v242, s[94:95]
	s_add_u32 m0, s49, 0xc3c0
	s_nop 0
	global_load_lds_dwordx4 v242, s[94:95] offset:64
	s_add_u32 s36, s36, 0x80
	s_xor_b32 s37, s36, 0x800
	s_add_u32 s98, s98, 128
	s_addc_u32 s99, s99, 0
	s_add_u32 s44, s44, 128
	s_addc_u32 s45, s45, 0
	s_waitcnt lgkmcnt(2)
	s_setprio 1
	v_mfma_f32_32x32x16_bf16 v[112:127], v[214:217], v[206:209], v[112:127]
	v_mfma_f32_32x32x16_bf16 v[96:111], v[214:217], v[210:213], v[96:111]
	v_mfma_f32_32x32x16_bf16 v[80:95], v[218:221], v[206:209], v[80:95]
	v_mfma_f32_32x32x16_bf16 v[64:79], v[218:221], v[210:213], v[64:79]
	s_setprio 0
	s_waitcnt vmcnt(0) lgkmcnt(0)
	s_barrier
	ds_read_b128 v[170:173], v232 offset:24576
	ds_read_b128 v[174:177], v232 offset:26624
	ds_read_b128 v[178:181], v230 offset:24576
	ds_read_b128 v[182:185], v230 offset:26624
	ds_read_b128 v[186:189], v230 offset:28672
	ds_read_b128 v[190:193], v230 offset:30720
	s_setprio 1
	v_mfma_f32_32x32x16_bf16 v[48:63], v[222:225], v[206:209], v[48:63]
	v_mfma_f32_32x32x16_bf16 v[32:47], v[222:225], v[210:213], v[32:47]
	v_mfma_f32_32x32x16_bf16 v[16:31], v[226:229], v[206:209], v[16:31]
	v_mfma_f32_32x32x16_bf16 v[0:15], v[226:229], v[210:213], v[0:15]
	s_setprio 0
	s_waitcnt lgkmcnt(2)
	s_setprio 1
	v_mfma_f32_32x32x16_bf16 v[112:127], v[178:181], v[170:173], v[112:127]
	v_mfma_f32_32x32x16_bf16 v[96:111], v[178:181], v[174:177], v[96:111]
	v_mfma_f32_32x32x16_bf16 v[80:95], v[182:185], v[170:173], v[80:95]
	v_mfma_f32_32x32x16_bf16 v[64:79], v[182:185], v[174:177], v[64:79]
	s_setprio 0
	ds_read_b128 v[206:209], v233 offset:24576
	ds_read_b128 v[210:213], v233 offset:26624
	ds_read_b128 v[214:217], v231 offset:24576
	ds_read_b128 v[218:221], v231 offset:26624
	s_waitcnt lgkmcnt(4)
	s_setprio 1
	v_mfma_f32_32x32x16_bf16 v[48:63], v[186:189], v[170:173], v[48:63]
	v_mfma_f32_32x32x16_bf16 v[32:47], v[186:189], v[174:177], v[32:47]
	v_mfma_f32_32x32x16_bf16 v[16:31], v[190:193], v[170:173], v[16:31]
	v_mfma_f32_32x32x16_bf16 v[0:15], v[190:193], v[174:177], v[0:15]
	s_setprio 0
	ds_read_b128 v[222:225], v231 offset:28672
	ds_read_b128 v[226:229], v231 offset:30720
	s_waitcnt lgkmcnt(2)
	s_setprio 1
	v_mfma_f32_32x32x16_bf16 v[112:127], v[214:217], v[206:209], v[112:127]
	v_mfma_f32_32x32x16_bf16 v[96:111], v[214:217], v[210:213], v[96:111]
	v_mfma_f32_32x32x16_bf16 v[80:95], v[218:221], v[206:209], v[80:95]
	v_mfma_f32_32x32x16_bf16 v[64:79], v[218:221], v[210:213], v[64:79]
	s_setprio 0
	s_waitcnt vmcnt(0) lgkmcnt(0)
	s_barrier
	ds_read_b128 v[170:173], v232 offset:49152
	ds_read_b128 v[174:177], v232 offset:51200
	ds_read_b128 v[178:181], v230 offset:49152
	ds_read_b128 v[182:185], v230 offset:51200
	ds_read_b128 v[186:189], v230 offset:53248
	ds_read_b128 v[190:193], v230 offset:55296
	s_setprio 1
	v_mfma_f32_32x32x16_bf16 v[48:63], v[222:225], v[206:209], v[48:63]
	v_mfma_f32_32x32x16_bf16 v[32:47], v[222:225], v[210:213], v[32:47]
	v_mfma_f32_32x32x16_bf16 v[16:31], v[226:229], v[206:209], v[16:31]
	v_mfma_f32_32x32x16_bf16 v[0:15], v[226:229], v[210:213], v[0:15]
	s_setprio 0
	s_add_u32 m0, s101, 0x0
	s_nop 0
	global_load_lds_dwordx4 v234, s[98:99]
	s_add_u32 m0, s101, 0x6000
	s_nop 0
	global_load_lds_dwordx4 v234, s[44:45]
	s_add_u32 m0, s101, 0x400
	s_nop 0
	global_load_lds_dwordx4 v235, s[98:99]
	s_add_u32 m0, s101, 0x6400
	s_nop 0
	global_load_lds_dwordx4 v235, s[44:45]
	s_waitcnt lgkmcnt(2)
	s_setprio 1
	v_mfma_f32_32x32x16_bf16 v[112:127], v[178:181], v[170:173], v[112:127]
	v_mfma_f32_32x32x16_bf16 v[96:111], v[178:181], v[174:177], v[96:111]
	v_mfma_f32_32x32x16_bf16 v[80:95], v[182:185], v[170:173], v[80:95]
	v_mfma_f32_32x32x16_bf16 v[64:79], v[182:185], v[174:177], v[64:79]
	s_setprio 0
	ds_read_b128 v[206:209], v233 offset:49152
	ds_read_b128 v[210:213], v233 offset:51200
	ds_read_b128 v[214:217], v231 offset:49152
	ds_read_b128 v[218:221], v231 offset:51200
	s_add_u32 m0, s101, 0x800
	s_nop 0
	global_load_lds_dwordx4 v236, s[98:99]
	s_add_u32 m0, s101, 0x6800
	s_nop 0
	global_load_lds_dwordx4 v236, s[44:45]
	s_add_u32 m0, s101, 0xc00
	s_nop 0
	global_load_lds_dwordx4 v237, s[98:99]
	s_add_u32 m0, s101, 0x6c00
	s_nop 0
	global_load_lds_dwordx4 v237, s[44:45]
	s_waitcnt lgkmcnt(4)
	s_setprio 1
	v_mfma_f32_32x32x16_bf16 v[48:63], v[186:189], v[170:173], v[48:63]
	v_mfma_f32_32x32x16_bf16 v[32:47], v[186:189], v[174:177], v[32:47]
	v_mfma_f32_32x32x16_bf16 v[16:31], v[190:193], v[170:173], v[16:31]
	v_mfma_f32_32x32x16_bf16 v[0:15], v[190:193], v[174:177], v[0:15]
	s_setprio 0
	ds_read_b128 v[222:225], v231 offset:53248
	ds_read_b128 v[226:229], v231 offset:55296
	v_xad_u32 v241, s36, v240, v238
	v_xad_u32 v242, s37, v240, v239
	s_add_u32 m0, s49, 0x0
	s_nop 0
	global_load_lds_dwordx4 v241, s[94:95]
	s_add_u32 m0, s49, 0x5fc0
	s_nop 0
	global_load_lds_dwordx4 v241, s[94:95] offset:64
	s_add_u32 m0, s49, 0x400
	s_nop 0
	global_load_lds_dwordx4 v242, s[94:95]
	s_add_u32 m0, s49, 0x63c0
	s_nop 0
	global_load_lds_dwordx4 v242, s[94:95] offset:64
	s_add_u32 s36, s36, 0x80
	s_xor_b32 s37, s36, 0x800
	s_add_u32 s98, s98, 128
	s_addc_u32 s99, s99, 0
	s_add_u32 s44, s44, 128
	s_addc_u32 s45, s45, 0
	s_waitcnt lgkmcnt(2)
	s_setprio 1
	v_mfma_f32_32x32x16_bf16 v[112:127], v[214:217], v[206:209], v[112:127]
	v_mfma_f32_32x32x16_bf16 v[96:111], v[214:217], v[210:213], v[96:111]
	v_mfma_f32_32x32x16_bf16 v[80:95], v[218:221], v[206:209], v[80:95]
	v_mfma_f32_32x32x16_bf16 v[64:79], v[218:221], v[210:213], v[64:79]
	s_setprio 0
	s_waitcnt vmcnt(0) lgkmcnt(0)
	s_barrier
	ds_read_b128 v[170:173], v232 offset:0
	ds_read_b128 v[174:177], v232 offset:2048
	ds_read_b128 v[178:181], v230 offset:0
	ds_read_b128 v[182:185], v230 offset:2048
	ds_read_b128 v[186:189], v230 offset:4096
	ds_read_b128 v[190:193], v230 offset:6144
	s_setprio 1
	v_mfma_f32_32x32x16_bf16 v[48:63], v[222:225], v[206:209], v[48:63]
	v_mfma_f32_32x32x16_bf16 v[32:47], v[222:225], v[210:213], v[32:47]
	v_mfma_f32_32x32x16_bf16 v[16:31], v[226:229], v[206:209], v[16:31]
	v_mfma_f32_32x32x16_bf16 v[0:15], v[226:229], v[210:213], v[0:15]
	s_setprio 0
	s_waitcnt lgkmcnt(2)
	s_setprio 1
	v_mfma_f32_32x32x16_bf16 v[112:127], v[178:181], v[170:173], v[112:127]
	v_mfma_f32_32x32x16_bf16 v[96:111], v[178:181], v[174:177], v[96:111]
	v_mfma_f32_32x32x16_bf16 v[80:95], v[182:185], v[170:173], v[80:95]
	v_mfma_f32_32x32x16_bf16 v[64:79], v[182:185], v[174:177], v[64:79]
	s_setprio 0
	ds_read_b128 v[206:209], v233 offset:0
	ds_read_b128 v[210:213], v233 offset:2048
	ds_read_b128 v[214:217], v231 offset:0
	ds_read_b128 v[218:221], v231 offset:2048
	s_waitcnt lgkmcnt(4)
	s_setprio 1
	v_mfma_f32_32x32x16_bf16 v[48:63], v[186:189], v[170:173], v[48:63]
	v_mfma_f32_32x32x16_bf16 v[32:47], v[186:189], v[174:177], v[32:47]
	v_mfma_f32_32x32x16_bf16 v[16:31], v[190:193], v[170:173], v[16:31]
	v_mfma_f32_32x32x16_bf16 v[0:15], v[190:193], v[174:177], v[0:15]
	s_setprio 0
	ds_read_b128 v[222:225], v231 offset:4096
	ds_read_b128 v[226:229], v231 offset:6144
	s_waitcnt lgkmcnt(2)
	s_setprio 1
	v_mfma_f32_32x32x16_bf16 v[112:127], v[214:217], v[206:209], v[112:127]
	v_mfma_f32_32x32x16_bf16 v[96:111], v[214:217], v[210:213], v[96:111]
	v_mfma_f32_32x32x16_bf16 v[80:95], v[218:221], v[206:209], v[80:95]
	v_mfma_f32_32x32x16_bf16 v[64:79], v[218:221], v[210:213], v[64:79]
	s_setprio 0
	s_sub_u32 s100, s100, 1
	s_cmp_lg_u32 s100, 0
	s_cbranch_scc1 .Lp1m_kloop
	s_waitcnt vmcnt(0) lgkmcnt(0)
	s_barrier
	ds_read_b128 v[170:173], v232 offset:24576
	ds_read_b128 v[174:177], v232 offset:26624
	ds_read_b128 v[178:181], v230 offset:24576
	ds_read_b128 v[182:185], v230 offset:26624
	ds_read_b128 v[186:189], v230 offset:28672
	ds_read_b128 v[190:193], v230 offset:30720
	s_setprio 1
	v_mfma_f32_32x32x16_bf16 v[48:63], v[222:225], v[206:209], v[48:63]
	v_mfma_f32_32x32x16_bf16 v[32:47], v[222:225], v[210:213], v[32:47]
	v_mfma_f32_32x32x16_bf16 v[16:31], v[226:229], v[206:209], v[16:31]
	v_mfma_f32_32x32x16_bf16 v[0:15], v[226:229], v[210:213], v[0:15]
	s_setprio 0
	s_add_u32 m0, s101, 0xc000
	s_nop 0
	global_load_lds_dwordx4 v234, s[98:99]
	s_add_u32 m0, s101, 0x0
	s_nop 0
	global_load_lds_dwordx4 v234, s[44:45]
	s_add_u32 m0, s101, 0xc400
	s_nop 0
	global_load_lds_dwordx4 v235, s[98:99]
	s_add_u32 m0, s101, 0x400
	s_nop 0
	global_load_lds_dwordx4 v235, s[44:45]
	s_waitcnt lgkmcnt(2)
	s_setprio 1
	v_mfma_f32_32x32x16_bf16 v[112:127], v[178:181], v[170:173], v[112:127]
	v_mfma_f32_32x32x16_bf16 v[96:111], v[178:181], v[174:177], v[96:111]
	v_mfma_f32_32x32x16_bf16 v[80:95], v[182:185], v[170:173], v[80:95]
	v_mfma_f32_32x32x16_bf16 v[64:79], v[182:185], v[174:177], v[64:79]
	s_setprio 0
	ds_read_b128 v[206:209], v233 offset:24576
	ds_read_b128 v[210:213], v233 offset:26624
	ds_read_b128 v[214:217], v231 offset:24576
	ds_read_b128 v[218:221], v231 offset:26624
	s_add_u32 m0, s101, 0xc800
	s_nop 0
	global_load_lds_dwordx4 v236, s[98:99]
	s_add_u32 m0, s101, 0x800
	s_nop 0
	global_load_lds_dwordx4 v236, s[44:45]
	s_add_u32 m0, s101, 0xcc00
	s_nop 0
	global_load_lds_dwordx4 v237, s[98:99]
	s_add_u32 m0, s101, 0xc00
	s_nop 0
	global_load_lds_dwordx4 v237, s[44:45]
	s_waitcnt lgkmcnt(4)
	s_setprio 1
	v_mfma_f32_32x32x16_bf16 v[48:63], v[186:189], v[170:173], v[48:63]
	v_mfma_f32_32x32x16_bf16 v[32:47], v[186:189], v[174:177], v[32:47]
	v_mfma_f32_32x32x16_bf16 v[16:31], v[190:193], v[170:173], v[16:31]
	v_mfma_f32_32x32x16_bf16 v[0:15], v[190:193], v[174:177], v[0:15]
	s_setprio 0
	ds_read_b128 v[222:225], v231 offset:28672
	ds_read_b128 v[226:229], v231 offset:30720
	v_xad_u32 v241, s36, v240, v238
	v_xad_u32 v242, s37, v240, v239
	s_add_u32 m0, s49, 0xc000
	s_nop 0
	global_load_lds_dwordx4 v241, s[94:95]
	s_add_u32 m0, s49, 0xffffffc0
	s_nop 0
	global_load_lds_dwordx4 v241, s[94:95] offset:64
	s_add_u32 m0, s49, 0xc400
	s_nop 0
	global_load_lds_dwordx4 v242, s[94:95]
	s_add_u32 m0, s49, 0x3c0
	s_nop 0
	global_load_lds_dwordx4 v242, s[94:95] offset:64
	s_add_u32 s36, s36, 0x80
	s_xor_b32 s37, s36, 0x800
	s_add_u32 s98, s98, 128
	s_addc_u32 s99, s99, 0
	s_add_u32 s44, s44, 128
	s_addc_u32 s45, s45, 0
	s_waitcnt lgkmcnt(2)
	s_setprio 1
	v_mfma_f32_32x32x16_bf16 v[112:127], v[214:217], v[206:209], v[112:127]
	v_mfma_f32_32x32x16_bf16 v[96:111], v[214:217], v[210:213], v[96:111]
	v_mfma_f32_32x32x16_bf16 v[80:95], v[218:221], v[206:209], v[80:95]
	v_mfma_f32_32x32x16_bf16 v[64:79], v[218:221], v[210:213], v[64:79]
	s_setprio 0
	s_waitcnt vmcnt(0) lgkmcnt(0)
	s_barrier
	ds_read_b128 v[170:173], v232 offset:49152
	ds_read_b128 v[174:177], v232 offset:51200
	ds_read_b128 v[178:181], v230 offset:49152
	ds_read_b128 v[182:185], v230 offset:51200
	ds_read_b128 v[186:189], v230 offset:53248
	ds_read_b128 v[190:193], v230 offset:55296
	s_setprio 1
	v_mfma_f32_32x32x16_bf16 v[48:63], v[222:225], v[206:209], v[48:63]
	v_mfma_f32_32x32x16_bf16 v[32:47], v[222:225], v[210:213], v[32:47]
	v_mfma_f32_32x32x16_bf16 v[16:31], v[226:229], v[206:209], v[16:31]
	v_mfma_f32_32x32x16_bf16 v[0:15], v[226:229], v[210:213], v[0:15]
	s_setprio 0
	s_waitcnt lgkmcnt(2)
	s_setprio 1
	v_mfma_f32_32x32x16_bf16 v[112:127], v[178:181], v[170:173], v[112:127]
	v_mfma_f32_32x32x16_bf16 v[96:111], v[178:181], v[174:177], v[96:111]
	v_mfma_f32_32x32x16_bf16 v[80:95], v[182:185], v[170:173], v[80:95]
	v_mfma_f32_32x32x16_bf16 v[64:79], v[182:185], v[174:177], v[64:79]
	s_setprio 0
	ds_read_b128 v[206:209], v233 offset:49152
	ds_read_b128 v[210:213], v233 offset:51200
	ds_read_b128 v[214:217], v231 offset:49152
	ds_read_b128 v[218:221], v231 offset:51200
	s_waitcnt lgkmcnt(4)
	s_setprio 1
	v_mfma_f32_32x32x16_bf16 v[48:63], v[186:189], v[170:173], v[48:63]
	v_mfma_f32_32x32x16_bf16 v[32:47], v[186:189], v[174:177], v[32:47]
	v_mfma_f32_32x32x16_bf16 v[16:31], v[190:193], v[170:173], v[16:31]
	v_mfma_f32_32x32x16_bf16 v[0:15], v[190:193], v[174:177], v[0:15]
	s_setprio 0
	ds_read_b128 v[222:225], v231 offset:53248
	ds_read_b128 v[226:229], v231 offset:55296
	s_waitcnt lgkmcnt(2)
	s_setprio 1
	v_mfma_f32_32x32x16_bf16 v[112:127], v[214:217], v[206:209], v[112:127]
	v_mfma_f32_32x32x16_bf16 v[96:111], v[214:217], v[210:213], v[96:111]
	v_mfma_f32_32x32x16_bf16 v[80:95], v[218:221], v[206:209], v[80:95]
	v_mfma_f32_32x32x16_bf16 v[64:79], v[218:221], v[210:213], v[64:79]
	s_setprio 0
	s_waitcnt vmcnt(0) lgkmcnt(0)
	s_barrier
	ds_read_b128 v[170:173], v232 offset:0
	ds_read_b128 v[174:177], v232 offset:2048
	ds_read_b128 v[178:181], v230 offset:0
	ds_read_b128 v[182:185], v230 offset:2048
	ds_read_b128 v[186:189], v230 offset:4096
	ds_read_b128 v[190:193], v230 offset:6144
	s_setprio 1
	v_mfma_f32_32x32x16_bf16 v[48:63], v[222:225], v[206:209], v[48:63]
	v_mfma_f32_32x32x16_bf16 v[32:47], v[222:225], v[210:213], v[32:47]
	v_mfma_f32_32x32x16_bf16 v[16:31], v[226:229], v[206:209], v[16:31]
	v_mfma_f32_32x32x16_bf16 v[0:15], v[226:229], v[210:213], v[0:15]
	s_setprio 0
	s_waitcnt lgkmcnt(2)
	s_setprio 1
	v_mfma_f32_32x32x16_bf16 v[112:127], v[178:181], v[170:173], v[112:127]
	v_mfma_f32_32x32x16_bf16 v[96:111], v[178:181], v[174:177], v[96:111]
	v_mfma_f32_32x32x16_bf16 v[80:95], v[182:185], v[170:173], v[80:95]
	v_mfma_f32_32x32x16_bf16 v[64:79], v[182:185], v[174:177], v[64:79]
	s_setprio 0
	ds_read_b128 v[206:209], v233 offset:0
	ds_read_b128 v[210:213], v233 offset:2048
	ds_read_b128 v[214:217], v231 offset:0
	ds_read_b128 v[218:221], v231 offset:2048
	s_waitcnt lgkmcnt(4)
	s_setprio 1
	v_mfma_f32_32x32x16_bf16 v[48:63], v[186:189], v[170:173], v[48:63]
	v_mfma_f32_32x32x16_bf16 v[32:47], v[186:189], v[174:177], v[32:47]
	v_mfma_f32_32x32x16_bf16 v[16:31], v[190:193], v[170:173], v[16:31]
	v_mfma_f32_32x32x16_bf16 v[0:15], v[190:193], v[174:177], v[0:15]
	s_setprio 0
	ds_read_b128 v[222:225], v231 offset:4096
	ds_read_b128 v[226:229], v231 offset:6144
	s_waitcnt lgkmcnt(2)
	s_setprio 1
	v_mfma_f32_32x32x16_bf16 v[112:127], v[214:217], v[206:209], v[112:127]
	v_mfma_f32_32x32x16_bf16 v[96:111], v[214:217], v[210:213], v[96:111]
	v_mfma_f32_32x32x16_bf16 v[80:95], v[218:221], v[206:209], v[80:95]
	v_mfma_f32_32x32x16_bf16 v[64:79], v[218:221], v[210:213], v[64:79]
	s_setprio 0
	s_waitcnt lgkmcnt(0)
	s_setprio 1
	v_mfma_f32_32x32x16_bf16 v[48:63], v[222:225], v[206:209], v[48:63]
	v_mfma_f32_32x32x16_bf16 v[32:47], v[222:225], v[210:213], v[32:47]
	v_mfma_f32_32x32x16_bf16 v[16:31], v[226:229], v[206:209], v[16:31]
	v_mfma_f32_32x32x16_bf16 v[0:15], v[226:229], v[210:213], v[0:15]
	s_setprio 0
	s_mul_hi_i32 s41, s42, 0x540000
	s_mul_i32 s42, s42, 0x540000
	s_add_u32 s42, s31, s42
	s_addc_u32 s43, s33, s41
	s_lshl_b32 s40, s40, 8
	s_add_u32 s42, s42, s40
	s_addc_u32 s43, s43, 0
	s_add_i32 s16, s16, s17
	s_add_i32 s47, s47, s17
	v_lshrrev_b32_e32 v170, 6, v204
	v_and_b32_e32 v171, 31, v204
	v_bfe_u32 v172, v204, 5, 1
	v_mul_u32_u24_e32 v173, 0x4400, v170
	v_mul_u32_u24_e32 v174, 544, v172
	v_lshl_add_u32 v174, v171, 2, v174
	v_add3_u32 v174, v174, v173, 32
	v_and_b32_e32 v175, 7, v204
	v_bfe_u32 v176, v204, 3, 3
	v_mul_u32_u24_e32 v177, 272, v176
	v_lshl_add_u32 v177, v175, 5, v177
	v_add3_u32 v177, v177, v173, 32
	v_lshrrev_b32_e32 v178, 1, v170
	v_and_b32_e32 v179, 1, v170
	v_lshlrev_b32_e32 v178, 7, v178
	v_lshl_add_u32 v178, v176, 1, v178
	v_mul_u32_u24_e32 v178, 0x5400, v178
	v_lshl_add_u32 v178, v179, 7, v178
	v_lshl_add_u32 v178, v175, 4, v178
	v_add_u32_e32 v179, 0x5400, v178
	v_mov_b32_e32 v180, 0x05040100
	v_mov_b32_e32 v181, 0x07060302
	s_waitcnt vmcnt(0)
	s_barrier
	v_cvt_pk_bf16_f32 v112, v112, v113
	ds_write_b32 v174, v112 offset:0
	v_cvt_pk_bf16_f32 v114, v114, v115
	ds_write_b32 v174, v114 offset:272
	v_cvt_pk_bf16_f32 v116, v116, v117
	ds_write_b32 v174, v116 offset:1088
	v_cvt_pk_bf16_f32 v118, v118, v119
	ds_write_b32 v174, v118 offset:1360
	v_cvt_pk_bf16_f32 v120, v120, v121
	ds_write_b32 v174, v120 offset:2176
	v_cvt_pk_bf16_f32 v122, v122, v123
	ds_write_b32 v174, v122 offset:2448
	v_cvt_pk_bf16_f32 v124, v124, v125
	ds_write_b32 v174, v124 offset:3264
	v_cvt_pk_bf16_f32 v126, v126, v127
	ds_write_b32 v174, v126 offset:3536
	v_cvt_pk_bf16_f32 v96, v96, v97
	ds_write_b32 v174, v96 offset:128
	v_cvt_pk_bf16_f32 v98, v98, v99
	ds_write_b32 v174, v98 offset:400
	v_cvt_pk_bf16_f32 v100, v100, v101
	ds_write_b32 v174, v100 offset:1216
	v_cvt_pk_bf16_f32 v102, v102, v103
	ds_write_b32 v174, v102 offset:1488
	v_cvt_pk_bf16_f32 v104, v104, v105
	ds_write_b32 v174, v104 offset:2304
	v_cvt_pk_bf16_f32 v106, v106, v107
	ds_write_b32 v174, v106 offset:2576
	v_cvt_pk_bf16_f32 v108, v108, v109
	ds_write_b32 v174, v108 offset:3392
	v_cvt_pk_bf16_f32 v110, v110, v111
	ds_write_b32 v174, v110 offset:3664
	v_cvt_pk_bf16_f32 v80, v80, v81
	ds_write_b32 v174, v80 offset:4352
	v_cvt_pk_bf16_f32 v82, v82, v83
	ds_write_b32 v174, v82 offset:4624
	v_cvt_pk_bf16_f32 v84, v84, v85
	ds_write_b32 v174, v84 offset:5440
	v_cvt_pk_bf16_f32 v86, v86, v87
	ds_write_b32 v174, v86 offset:5712
	v_cvt_pk_bf16_f32 v88, v88, v89
	ds_write_b32 v174, v88 offset:6528
	v_cvt_pk_bf16_f32 v90, v90, v91
	ds_write_b32 v174, v90 offset:6800
	v_cvt_pk_bf16_f32 v92, v92, v93
	ds_write_b32 v174, v92 offset:7616
	v_cvt_pk_bf16_f32 v94, v94, v95
	ds_write_b32 v174, v94 offset:7888
	v_cvt_pk_bf16_f32 v64, v64, v65
	ds_write_b32 v174, v64 offset:4480
	v_cvt_pk_bf16_f32 v66, v66, v67
	ds_write_b32 v174, v66 offset:4752
	v_cvt_pk_bf16_f32 v68, v68, v69
	ds_write_b32 v174, v68 offset:5568
	v_cvt_pk_bf16_f32 v70, v70, v71
	ds_write_b32 v174, v70 offset:5840
	v_cvt_pk_bf16_f32 v72, v72, v73
	ds_write_b32 v174, v72 offset:6656
	v_cvt_pk_bf16_f32 v74, v74, v75
	ds_write_b32 v174, v74 offset:6928
	v_cvt_pk_bf16_f32 v76, v76, v77
	ds_write_b32 v174, v76 offset:7744
	v_cvt_pk_bf16_f32 v78, v78, v79
	ds_write_b32 v174, v78 offset:8016
	v_cvt_pk_bf16_f32 v48, v48, v49
	ds_write_b32 v174, v48 offset:8704
	v_cvt_pk_bf16_f32 v50, v50, v51
	ds_write_b32 v174, v50 offset:8976
	v_cvt_pk_bf16_f32 v52, v52, v53
	ds_write_b32 v174, v52 offset:9792
	v_cvt_pk_bf16_f32 v54, v54, v55
	ds_write_b32 v174, v54 offset:10064
	v_cvt_pk_bf16_f32 v56, v56, v57
	ds_write_b32 v174, v56 offset:10880
	v_cvt_pk_bf16_f32 v58, v58, v59
	ds_write_b32 v174, v58 offset:11152
	v_cvt_pk_bf16_f32 v60, v60, v61
	ds_write_b32 v174, v60 offset:11968
	v_cvt_pk_bf16_f32 v62, v62, v63
	ds_write_b32 v174, v62 offset:12240
	v_cvt_pk_bf16_f32 v32, v32, v33
	ds_write_b32 v174, v32 offset:8832
	v_cvt_pk_bf16_f32 v34, v34, v35
	ds_write_b32 v174, v34 offset:9104
	v_cvt_pk_bf16_f32 v36, v36, v37
	ds_write_b32 v174, v36 offset:9920
	v_cvt_pk_bf16_f32 v38, v38, v39
	ds_write_b32 v174, v38 offset:10192
	v_cvt_pk_bf16_f32 v40, v40, v41
	ds_write_b32 v174, v40 offset:11008
	v_cvt_pk_bf16_f32 v42, v42, v43
	ds_write_b32 v174, v42 offset:11280
	v_cvt_pk_bf16_f32 v44, v44, v45
	ds_write_b32 v174, v44 offset:12096
	v_cvt_pk_bf16_f32 v46, v46, v47
	ds_write_b32 v174, v46 offset:12368
	v_cvt_pk_bf16_f32 v16, v16, v17
	ds_write_b32 v174, v16 offset:13056
	v_cvt_pk_bf16_f32 v18, v18, v19
	ds_write_b32 v174, v18 offset:13328
	v_cvt_pk_bf16_f32 v20, v20, v21
	ds_write_b32 v174, v20 offset:14144
	v_cvt_pk_bf16_f32 v22, v22, v23
	ds_write_b32 v174, v22 offset:14416
	v_cvt_pk_bf16_f32 v24, v24, v25
	ds_write_b32 v174, v24 offset:15232
	v_cvt_pk_bf16_f32 v26, v26, v27
	ds_write_b32 v174, v26 offset:15504
	v_cvt_pk_bf16_f32 v28, v28, v29
	ds_write_b32 v174, v28 offset:16320
	v_cvt_pk_bf16_f32 v30, v30, v31
	ds_write_b32 v174, v30 offset:16592
	v_cvt_pk_bf16_f32 v0, v0, v1
	ds_write_b32 v174, v0 offset:13184
	v_cvt_pk_bf16_f32 v2, v2, v3
	ds_write_b32 v174, v2 offset:13456
	v_cvt_pk_bf16_f32 v4, v4, v5
	ds_write_b32 v174, v4 offset:14272
	v_cvt_pk_bf16_f32 v6, v6, v7
	ds_write_b32 v174, v6 offset:14544
	v_cvt_pk_bf16_f32 v8, v8, v9
	ds_write_b32 v174, v8 offset:15360
	v_cvt_pk_bf16_f32 v10, v10, v11
	ds_write_b32 v174, v10 offset:15632
	v_cvt_pk_bf16_f32 v12, v12, v13
	ds_write_b32 v174, v12 offset:16448
	v_cvt_pk_bf16_f32 v14, v14, v15
	ds_write_b32 v174, v14 offset:16720
	s_cmp_ge_i32 s16, s22
	s_cselect_b64 s[40:41], -1, 0
	s_waitcnt lgkmcnt(0)
	ds_read_b128 v[182:185], v177 offset:0
	ds_read_b128 v[186:189], v177 offset:16
	ds_read_b128 v[190:193], v177 offset:2176
	ds_read_b128 v[194:197], v177 offset:2192
	s_waitcnt lgkmcnt(2)
	v_perm_b32 v198, v183, v182, v180
	v_perm_b32 v199, v185, v184, v180
	v_perm_b32 v200, v187, v186, v180
	v_perm_b32 v201, v189, v188, v180
	v_perm_b32 v206, v183, v182, v181
	v_perm_b32 v207, v185, v184, v181
	v_perm_b32 v208, v187, v186, v181
	v_perm_b32 v209, v189, v188, v181
	global_store_dwordx4 v178, v[198:201], s[42:43] nt
	global_store_dwordx4 v179, v[206:209], s[42:43] nt
	s_add_u32 s42, s42, 0x54000
	s_addc_u32 s43, s43, 0
	s_nop 1
	ds_read_b128 v[182:185], v177 offset:4352
	ds_read_b128 v[186:189], v177 offset:4368
	s_waitcnt lgkmcnt(2)
	v_perm_b32 v198, v191, v190, v180
	v_perm_b32 v199, v193, v192, v180
	v_perm_b32 v200, v195, v194, v180
	v_perm_b32 v201, v197, v196, v180
	v_perm_b32 v206, v191, v190, v181
	v_perm_b32 v207, v193, v192, v181
	v_perm_b32 v208, v195, v194, v181
	v_perm_b32 v209, v197, v196, v181
	global_store_dwordx4 v178, v[198:201], s[42:43] nt
	global_store_dwordx4 v179, v[206:209], s[42:43] nt
	s_add_u32 s42, s42, 0x54000
	s_addc_u32 s43, s43, 0
	s_nop 1
	ds_read_b128 v[190:193], v177 offset:6528
	ds_read_b128 v[194:197], v177 offset:6544
	s_waitcnt lgkmcnt(2)
	v_perm_b32 v198, v183, v182, v180
	v_perm_b32 v199, v185, v184, v180
	v_perm_b32 v200, v187, v186, v180
	v_perm_b32 v201, v189, v188, v180
	v_perm_b32 v206, v183, v182, v181
	v_perm_b32 v207, v185, v184, v181
	v_perm_b32 v208, v187, v186, v181
	v_perm_b32 v209, v189, v188, v181
	global_store_dwordx4 v178, v[198:201], s[42:43] nt
	global_store_dwordx4 v179, v[206:209], s[42:43] nt
	s_add_u32 s42, s42, 0x54000
	s_addc_u32 s43, s43, 0
	s_nop 1
	ds_read_b128 v[182:185], v177 offset:8704
	ds_read_b128 v[186:189], v177 offset:8720
	s_waitcnt lgkmcnt(2)
	v_perm_b32 v198, v191, v190, v180
	v_perm_b32 v199, v193, v192, v180
	v_perm_b32 v200, v195, v194, v180
	v_perm_b32 v201, v197, v196, v180
	v_perm_b32 v206, v191, v190, v181
	v_perm_b32 v207, v193, v192, v181
	v_perm_b32 v208, v195, v194, v181
	v_perm_b32 v209, v197, v196, v181
	global_store_dwordx4 v178, v[198:201], s[42:43] nt
	global_store_dwordx4 v179, v[206:209], s[42:43] nt
	s_add_u32 s42, s42, 0x54000
	s_addc_u32 s43, s43, 0
	s_nop 1
	ds_read_b128 v[190:193], v177 offset:10880
	ds_read_b128 v[194:197], v177 offset:10896
	s_waitcnt lgkmcnt(2)
	v_perm_b32 v198, v183, v182, v180
	v_perm_b32 v199, v185, v184, v180
	v_perm_b32 v200, v187, v186, v180
	v_perm_b32 v201, v189, v188, v180
	v_perm_b32 v206, v183, v182, v181
	v_perm_b32 v207, v185, v184, v181
	v_perm_b32 v208, v187, v186, v181
	v_perm_b32 v209, v189, v188, v181
	global_store_dwordx4 v178, v[198:201], s[42:43] nt
	global_store_dwordx4 v179, v[206:209], s[42:43] nt
	s_add_u32 s42, s42, 0x54000
	s_addc_u32 s43, s43, 0
	s_nop 1
	ds_read_b128 v[182:185], v177 offset:13056
	ds_read_b128 v[186:189], v177 offset:13072
	s_waitcnt lgkmcnt(2)
	v_perm_b32 v198, v191, v190, v180
	v_perm_b32 v199, v193, v192, v180
	v_perm_b32 v200, v195, v194, v180
	v_perm_b32 v201, v197, v196, v180
	v_perm_b32 v206, v191, v190, v181
	v_perm_b32 v207, v193, v192, v181
	v_perm_b32 v208, v195, v194, v181
	v_perm_b32 v209, v197, v196, v181
	global_store_dwordx4 v178, v[198:201], s[42:43] nt
	global_store_dwordx4 v179, v[206:209], s[42:43] nt
	s_add_u32 s42, s42, 0x54000
	s_addc_u32 s43, s43, 0
	s_nop 1
	ds_read_b128 v[190:193], v177 offset:15232
	ds_read_b128 v[194:197], v177 offset:15248
	s_waitcnt lgkmcnt(2)
	v_perm_b32 v198, v183, v182, v180
	v_perm_b32 v199, v185, v184, v180
	v_perm_b32 v200, v187, v186, v180
	v_perm_b32 v201, v189, v188, v180
	v_perm_b32 v206, v183, v182, v181
	v_perm_b32 v207, v185, v184, v181
	v_perm_b32 v208, v187, v186, v181
	v_perm_b32 v209, v189, v188, v181
	global_store_dwordx4 v178, v[198:201], s[42:43] nt
	global_store_dwordx4 v179, v[206:209], s[42:43] nt
	s_add_u32 s42, s42, 0x54000
	s_addc_u32 s43, s43, 0
	s_nop 1
	s_waitcnt lgkmcnt(0)
	s_barrier
	v_perm_b32 v198, v191, v190, v180
	v_perm_b32 v199, v193, v192, v180
	v_perm_b32 v200, v195, v194, v180
	v_perm_b32 v201, v197, v196, v180
	v_perm_b32 v206, v191, v190, v181
	v_perm_b32 v207, v193, v192, v181
	v_perm_b32 v208, v195, v194, v181
	v_perm_b32 v209, v197, v196, v181
	global_store_dwordx4 v178, v[198:201], s[42:43] nt
	global_store_dwordx4 v179, v[206:209], s[42:43] nt
	s_branch .LBB0_126
